# GEMM-in column-tile rounds reordered (merge first, C-mixer inputs last) for memory-side cache residency; mixA V frags via dwordx4+permlane32_swap; dropped post-asm s_nop 0
# speedup vs baseline: 1.0038x; 1.0038x over previous
;     DI bool next(int i, pg8::Unit& u) const { pg8::Unit b; if (!so.next(i / 3, b)) return false; const int nb = i % 3; u.pm = b.pm + 32 * nb; u.pn = b.pn + 8 * nb; return true; }
;     DI bool next(int i, Unit& u) const {
;         const long L = (long)i * G + c; if (L >= nwg) return false;
;         int wgid = (int)L; { const int q = nwg / NXCD, r = nwg % NXCD, xcd = wgid % NXCD, off = wgid / NXCD; wgid = (xcd < r ? xcd * (q + 1) : r * (q + 1) + (xcd - r) * q) + off; }
;         const int nig = WGM * nN, gid = wgid / nig, fm = gid * WGM, gsz = (nM - fm) < WGM ? (nM - fm) : WGM;
;         u.pm = fm + ((wgid % nig) % gsz); u.pn = (wgid % nig) / gsz; return true;
.LBB0_342:
	s_add_i32 s74, s74, 1
	s_add_i32 s15, s74, 8
	s_cmpk_lt_i32 s74, 4
	s_cselect_b32 s15, s15, s74
	s_sub_i32 s11, s74, 3
	s_cmpk_gt_i32 s74, 3
	s_cselect_b32 s15, s11, s15
	s_cmpk_gt_i32 s74, 11
	s_cselect_b32 s15, s74, s15
	v_readlane_b32 s11, v253, 20
	v_readlane_b32 s14, v255, 31
	s_mul_i32 s11, s15, s11
	s_mul_hi_u32 s13, s15, s14
	s_add_i32 s13, s13, s11
	s_mul_i32 s11, s15, s14
	v_readlane_b32 s14, v253, 0
	s_add_u32 s14, s11, s14
	v_readlane_b32 s11, v253, 18
	s_addc_u32 s15, s13, s11
	v_mov_b64_e32 v[0:1], 0xbff
	v_cmp_gt_i64_e64 s[40:41], s[14:15], v[0:1]
	s_and_b64 vcc, exec, s[40:41]
	s_cbranch_vccnz .LBB0_344
	s_ashr_i32 s10, s14, 31
	s_lshr_b32 s10, s10, 29
	s_add_i32 s10, s14, s10
	s_ashr_i32 s11, s10, 3
	s_and_b32 s10, s10, -8
	s_sub_i32 s10, s14, s10
	s_cmp_lt_i32 s10, 0
	s_movk_i32 s12, 0x181
	s_cselect_b32 s12, s12, 0x180
	s_mul_i32 s10, s12, s10
	s_add_i32 s10, s10, s11
	s_mul_hi_i32 s11, s10, 0x2aaaaaab
	s_lshr_b32 s12, s11, 31
	s_ashr_i32 s11, s11, 6
	s_add_i32 s11, s11, s12
	s_lshl_b32 s12, s11, 2
	s_sub_i32 s13, 32, s12
	s_min_i32 s13, s13, 4
	s_abs_i32 s16, s13
	v_cvt_f32_u32_e32 v0, s16
	s_sub_i32 s24, 0, s16
	s_mulk_i32 s11, 0x180
	s_sub_i32 s11, s10, s11
	v_rcp_iflag_f32_e32 v0, v0
	s_abs_i32 s10, s11
	s_xor_b32 s17, s11, s13
	s_ashr_i32 s17, s17, 31
	v_mul_f32_e32 v0, 0x4f7ffffe, v0
	v_cvt_u32_f32_e32 v0, v0
	s_nop 0
	v_readfirstlane_b32 s25, v0
	s_mul_i32 s24, s24, s25
	s_mul_hi_u32 s24, s25, s24
	s_add_i32 s25, s25, s24
	s_mul_hi_u32 s24, s10, s25
	s_mul_i32 s25, s24, s16
	s_sub_i32 s10, s10, s25
	s_add_i32 s26, s24, 1
	s_sub_i32 s25, s10, s16
	s_cmp_ge_u32 s10, s16
	s_cselect_b32 s24, s26, s24
	s_cselect_b32 s10, s25, s10
	s_add_i32 s25, s24, 1
	s_cmp_ge_u32 s10, s16
	s_cselect_b32 s10, s25, s24
	s_xor_b32 s10, s10, s17
	s_sub_i32 s10, s10, s17
	s_mul_i32 s13, s10, s13
	s_sub_i32 s11, s11, s13
	s_add_i32 s12, s11, s12
